# kind-0 gated epilogue: bf16 output blocks transposed via LDS so stores write 64B row segments by adjacent lanes
# baseline (speedup 1.0000x reference)
;     __device__ __forceinline__ void operator()(const f32x4 (&acc)[2][2][4][2], const Unit& u, int wr, int wc, int fr, int fq) const {
;     ...
;         const int row0 = u.pm * BM + wr * 64 + fr, bcol0 = u.pn * BM + wc * 32 + 8 * fq, ocol = u.pn * HALF + wc * 32 + 8 * fq;
;         constexpr float NL2E = -1.44269504f;
;         f32x2 b0[4], b1[4], bz[4];
; #pragma unroll
;         for (int n = 0; n < 2; ++n) { const f32x4 x0 = *(const f32x4*)(cb + bcol0 + 4 * n), x1 = *(const f32x4*)(cb + bcol0 + HALF + 4 * n);
;             b0[2 * n] = (f32x2){x0[0], x0[1]}; b0[2 * n + 1] = (f32x2){x0[2], x0[3]}; b1[2 * n] = (f32x2){x1[0], x1[1]}; b1[2 * n + 1] = (f32x2){x1[2], x1[3]}; }
; #pragma unroll
;         for (int p = 0; p < 4; ++p) bz[p] = (MODE == 0 ? b0[p] : b1[p]) * NL2E;
;         float sq[2][4];
; #pragma unroll
;         for (int ai = 0; ai < 2; ++ai)
; #pragma unroll
;             for (int m = 0; m < 4; ++m) sq[ai][m] = ssq[row0 + ai * HALF + m * 16];
; #pragma unroll
;         for (int ai = 0; ai < 2; ++ai)
; #pragma unroll
;             for (int m = 0; m < 4; ++m) {
;                 const int row = row0 + ai * HALF + m * 16;
;                 const float rs = __builtin_amdgcn_rsqf(sq[ai][m] * (1.0f / 1024.0f) + RMS_EPS_F), rz = rs * NL2E;
;                 unsigned w[4];
; #pragma unroll
;                 for (int p = 0; p < 4; ++p) {
;                     const f32x4 a0 = acc[ai][0][m][p >> 1], a1 = acc[ai][1][m][p >> 1];
;                     const f32x2 c0 = (p & 1) ? (f32x2){a0[2], a0[3]} : (f32x2){a0[0], a0[1]}, c1 = (p & 1) ? (f32x2){a1[2], a1[3]} : (f32x2){a1[0], a1[1]};
;                     const f32x2 v0 = c0 * rs + b0[p], v1 = c1 * rs + b1[p];
;                     const f32x2 t = (MODE == 0 ? c0 : c1) * rz + bz[p];
;                     f32x2 d; d.x = __builtin_amdgcn_exp2f(t.x); d.y = __builtin_amdgcn_exp2f(t.y); d = d + 1.0f;
;                     f32x2 r; r.x = __builtin_amdgcn_rcpf(d.x); r.y = __builtin_amdgcn_rcpf(d.y);
;                     const f32x2 o = (MODE == 0) ? (v0 * v1) * r : v0 * r;
;                     w[p] = cvt_pk_bf16(o.x, o.y);
;                 }
;                 u32x4 wv; wv.x = w[0]; wv.y = w[1]; wv.z = w[2]; wv.w = w[3];
;                 *(u32x4*)(O + ((unsigned)row * (unsigned)ldc + (unsigned)ocol)) = wv;
.LBB0_507:
	s_cmp_eq_u32 s0, 1
	s_mov_b64 s[42:43], -1
	s_cbranch_scc1 .LBB0_509
	s_mov_b64 s[44:45], s[72:73]
	s_mov_b64 s[60:61], s[56:57]
	s_mov_b64 s[42:43], s[24:25]
	s_mov_b64 s[64:65], s[76:77]
	s_cmp_gt_i32 s14, 63
	s_cselect_b32 s17, s61, s65
	s_cselect_b32 s60, s60, s64
	v_lshl_or_b32 v132, s15, 8, v229
	v_lshl_add_u32 v158, s14, 8, v1
	v_mov_b32_e32 v130, s60
	v_mov_b32_e32 v131, s17
	v_ashrrev_i32_e32 v133, 31, v132
	v_ashrrev_i32_e32 v159, 31, v158
	v_lshl_add_u64 v[142:143], v[132:133], 2, v[130:131]
	v_lshl_add_u64 v[146:147], v[158:159], 2, s[44:45]
	global_load_dwordx4 v[130:133], v[142:143], off offset:16
	global_load_dwordx4 v[138:141], v[142:143], off
	global_load_dwordx4 v[134:137], v[142:143], off offset:528
	s_nop 0
	global_load_dwordx4 v[142:145], v[142:143], off offset:512
	s_nop 0
	global_load_dword v148, v[146:147], off
	global_load_dword v174, v[146:147], off offset:64
	global_load_dword v167, v[146:147], off offset:128
	global_load_dword v166, v[146:147], off offset:192
	global_load_dword v165, v[146:147], off offset:512
	global_load_dword v164, v[146:147], off offset:576
	global_load_dword v163, v[146:147], off offset:640
	global_load_dword v161, v[146:147], off offset:704
	v_and_b32_e32 v178, 3, v227
	v_lshrrev_b32_e32 v179, 2, v227
	v_lshrrev_b32_e32 v180, 6, v1
	v_lshrrev_b32_e32 v181, 5, v229
	v_lshl_add_u32 v177, v180, 6, v179
	v_mul_lo_u32 v177, v177, s90
	v_lshl_add_u32 v177, v181, 5, v177
	v_lshl_add_u32 v177, v178, 3, v177
	v_lshlrev_b32_e32 v177, 1, v177
	v_lshl_add_u32 v180, v180, 2, v181
	v_mul_u32_u24_e32 v180, 0x900, v180
	v_add_u32_e32 v180, 0x22000, v180
	v_mul_u32_u24_e32 v176, 0x50, v179
	v_lshl_add_u32 v176, v178, 4, v176
	v_add_u32_e32 v176, v176, v180
	v_and_b32_e32 v175, 15, v227
	v_mul_u32_u24_e32 v175, 0x50, v175
	v_lshrrev_b32_e32 v178, 4, v227
	v_lshl_add_u32 v175, v178, 4, v175
	v_add_u32_e32 v175, v175, v180
	s_mul_i32 s65, s14, s90
	s_lshl_b32 s65, s65, 9
	s_lshl_b32 s64, s15, 8
	s_add_i32 s65, s65, s64
	s_add_u32 s60, s24, s65
	s_addc_u32 s61, s25, 0
	s_lshl_b32 s64, s90, 5
	v_lshl_or_b32 v160, s15, 7, v229
	s_mul_i32 s17, s90, 0x50
	s_waitcnt vmcnt(0)
	v_fmamk_f32 v146, v148, 0x3a800000, v213
	v_rsq_f32_e32 v162, v146
	v_pk_mul_f32 v[152:153], v[130:131], s[30:31] op_sel_hi:[1,0]
	v_pk_mul_f32 v[156:157], v[138:139], s[30:31] op_sel_hi:[1,0]
	v_mul_f32_e32 v168, 0xbfb8aa3b, v162
	v_pk_fma_f32 v[170:171], v[126:127], v[168:169], v[156:157] op_sel_hi:[1,0,1]
	v_pk_mul_f32 v[154:155], v[140:141], s[30:31] op_sel_hi:[1,0]
	v_exp_f32_e32 v170, v170
	v_exp_f32_e32 v171, v171
	v_pk_fma_f32 v[172:173], v[128:129], v[168:169], v[154:155] op_sel_hi:[1,0,1]
	v_pk_fma_f32 v[146:147], v[126:127], v[162:163], v[138:139] op_sel_hi:[1,0,1]
	v_exp_f32_e32 v172, v172
	v_exp_f32_e32 v173, v173
	v_pk_add_f32 v[170:171], v[170:171], 1.0 op_sel_hi:[1,0]
	v_pk_fma_f32 v[148:149], v[118:119], v[162:163], v[142:143] op_sel_hi:[1,0,1]
	v_rcp_f32_e32 v170, v170
	v_rcp_f32_e32 v171, v171
	v_pk_add_f32 v[172:173], v[172:173], 1.0 op_sel_hi:[1,0]
	v_pk_mul_f32 v[146:147], v[146:147], v[148:149]
	v_rcp_f32_e32 v172, v172
	v_rcp_f32_e32 v173, v173
	v_pk_mul_f32 v[146:147], v[146:147], v[170:171]
	v_pk_fma_f32 v[148:149], v[128:129], v[162:163], v[140:141] op_sel_hi:[1,0,1]
	v_pk_fma_f32 v[170:171], v[120:121], v[162:163], v[144:145] op_sel_hi:[1,0,1]
	v_pk_mul_f32 v[150:151], v[132:133], s[30:31] op_sel_hi:[1,0]
	v_pk_mul_f32 v[148:149], v[148:149], v[170:171]
	v_cvt_pk_bf16_f32 v146, v146, v147
	v_pk_fma_f32 v[170:171], v[114:115], v[162:163], v[134:135] op_sel_hi:[1,0,1]
	v_pk_mul_f32 v[148:149], v[148:149], v[172:173]
	v_pk_fma_f32 v[172:173], v[122:123], v[168:169], v[152:153] op_sel_hi:[1,0,1]
	v_pk_fma_f32 v[168:169], v[124:125], v[168:169], v[150:151] op_sel_hi:[1,0,1]
	v_exp_f32_e32 v172, v172
	v_exp_f32_e32 v173, v173
	v_exp_f32_e32 v168, v168
	v_exp_f32_e32 v169, v169
	v_cvt_pk_bf16_f32 v147, v148, v149
	v_pk_add_f32 v[172:173], v[172:173], 1.0 op_sel_hi:[1,0]
	v_pk_fma_f32 v[148:149], v[122:123], v[162:163], v[130:131] op_sel_hi:[1,0,1]
	v_rcp_f32_e32 v172, v172
	v_rcp_f32_e32 v173, v173
	v_pk_add_f32 v[168:169], v[168:169], 1.0 op_sel_hi:[1,0]
	v_pk_mul_f32 v[148:149], v[148:149], v[170:171]
	v_rcp_f32_e32 v168, v168
	v_rcp_f32_e32 v169, v169
	v_pk_mul_f32 v[148:149], v[148:149], v[172:173]
	v_pk_fma_f32 v[170:171], v[124:125], v[162:163], v[132:133] op_sel_hi:[1,0,1]
	v_pk_fma_f32 v[172:173], v[116:117], v[162:163], v[136:137] op_sel_hi:[1,0,1]
	v_mad_u64_u32 v[158:159], s[44:45], v158, s90, v[160:161]
	v_pk_mul_f32 v[170:171], v[170:171], v[172:173]
	v_mov_b32_e32 v159, v0
	v_pk_mul_f32 v[168:169], v[170:171], v[168:169]
	v_cvt_pk_bf16_f32 v148, v148, v149
	s_nop 0
	v_cvt_pk_bf16_f32 v149, v168, v169
	v_lshl_add_u64 v[168:169], v[158:159], 1, s[42:43]
	ds_write_b128 v175, v[146:149]
	ds_read_b128 v[196:199], v176
	v_add_u32_e32 v158, s12, v158
	s_nop 0
	v_fmamk_f32 v146, v174, 0x3a800000, v213
	v_rsq_f32_e32 v160, v146
	s_nop 0
	v_mul_f32_e32 v162, 0xbfb8aa3b, v160
	v_pk_fma_f32 v[168:169], v[110:111], v[162:163], v[156:157] op_sel_hi:[1,0,1]
	v_pk_fma_f32 v[170:171], v[112:113], v[162:163], v[154:155] op_sel_hi:[1,0,1]
	v_exp_f32_e32 v168, v168
	v_exp_f32_e32 v169, v169
	v_exp_f32_e32 v170, v170
	v_exp_f32_e32 v171, v171
	v_pk_fma_f32 v[146:147], v[110:111], v[160:161], v[138:139] op_sel_hi:[1,0,1]
	v_pk_add_f32 v[168:169], v[168:169], 1.0 op_sel_hi:[1,0]
	v_pk_fma_f32 v[148:149], v[106:107], v[160:161], v[142:143] op_sel_hi:[1,0,1]
	v_rcp_f32_e32 v168, v168
	v_rcp_f32_e32 v169, v169
	v_pk_add_f32 v[170:171], v[170:171], 1.0 op_sel_hi:[1,0]
	v_pk_mul_f32 v[146:147], v[146:147], v[148:149]
; __device__ __forceinline__ unsigned cvt_pk_bf16(float lo, float hi) { unsigned r; asm volatile("v_cvt_pk_bf16_f32 %0, %1, %2" : "=v"(r) : "v"(lo), "v"(hi)); return r; }
;     __device__ __forceinline__ void operator()(const f32x4 (&acc)[2][2][4][2], const Unit& u, int wr, int wc, int fr, int fq) const {
;     ...
;             for (int m = 0; m < 4; ++m) {
;                 const int row = row0 + ai * HALF + m * 16;
;                 const float rs = __builtin_amdgcn_rsqf(sq[ai][m] * (1.0f / 1024.0f) + RMS_EPS_F), rz = rs * NL2E;
;                 unsigned w[4];
; #pragma unroll
;                 for (int p = 0; p < 4; ++p) {
;                     const f32x4 a0 = acc[ai][0][m][p >> 1], a1 = acc[ai][1][m][p >> 1];
;                     const f32x2 c0 = (p & 1) ? (f32x2){a0[2], a0[3]} : (f32x2){a0[0], a0[1]}, c1 = (p & 1) ? (f32x2){a1[2], a1[3]} : (f32x2){a1[0], a1[1]};
;                     const f32x2 v0 = c0 * rs + b0[p], v1 = c1 * rs + b1[p];
;                     const f32x2 t = (MODE == 0 ? c0 : c1) * rz + bz[p];
;                     f32x2 d; d.x = __builtin_amdgcn_exp2f(t.x); d.y = __builtin_amdgcn_exp2f(t.y); d = d + 1.0f;
;                     f32x2 r; r.x = __builtin_amdgcn_rcpf(d.x); r.y = __builtin_amdgcn_rcpf(d.y);
;                     const f32x2 o = (MODE == 0) ? (v0 * v1) * r : v0 * r;
;                     w[p] = cvt_pk_bf16(o.x, o.y);
;                 }
;                 u32x4 wv; wv.x = w[0]; wv.y = w[1]; wv.z = w[2]; wv.w = w[3];
;                 *(u32x4*)(O + ((unsigned)row * (unsigned)ldc + (unsigned)ocol)) = wv;
	v_rcp_f32_e32 v170, v170
	v_rcp_f32_e32 v171, v171
	v_pk_mul_f32 v[146:147], v[146:147], v[168:169]
	v_pk_fma_f32 v[148:149], v[112:113], v[160:161], v[140:141] op_sel_hi:[1,0,1]
	v_pk_fma_f32 v[168:169], v[108:109], v[160:161], v[144:145] op_sel_hi:[1,0,1]
	v_pk_fma_f32 v[172:173], v[104:105], v[162:163], v[150:151] op_sel_hi:[1,0,1]
	v_pk_mul_f32 v[148:149], v[148:149], v[168:169]
	v_exp_f32_e32 v172, v172
	v_pk_mul_f32 v[148:149], v[148:149], v[170:171]
	v_pk_fma_f32 v[170:171], v[102:103], v[162:163], v[152:153] op_sel_hi:[1,0,1]
	v_exp_f32_e32 v173, v173
	v_exp_f32_e32 v170, v170
	v_exp_f32_e32 v171, v171
	v_cvt_pk_bf16_f32 v146, v146, v147
	v_pk_add_f32 v[172:173], v[172:173], 1.0 op_sel_hi:[1,0]
	v_cvt_pk_bf16_f32 v147, v148, v149
	v_pk_add_f32 v[170:171], v[170:171], 1.0 op_sel_hi:[1,0]
	v_pk_fma_f32 v[148:149], v[102:103], v[160:161], v[130:131] op_sel_hi:[1,0,1]
	v_rcp_f32_e32 v170, v170
	v_rcp_f32_e32 v171, v171
	v_pk_fma_f32 v[168:169], v[98:99], v[160:161], v[134:135] op_sel_hi:[1,0,1]
	v_rcp_f32_e32 v172, v172
	v_rcp_f32_e32 v173, v173
	v_pk_mul_f32 v[148:149], v[148:149], v[168:169]
	v_pk_fma_f32 v[168:169], v[104:105], v[160:161], v[132:133] op_sel_hi:[1,0,1]
	v_pk_mul_f32 v[148:149], v[148:149], v[170:171]
	v_pk_fma_f32 v[170:171], v[100:101], v[160:161], v[136:137] op_sel_hi:[1,0,1]
	v_cvt_pk_bf16_f32 v148, v148, v149
	s_nop 0
	v_pk_mul_f32 v[168:169], v[168:169], v[170:171]
	s_nop 0
	v_pk_mul_f32 v[168:169], v[168:169], v[172:173]
	s_nop 0
	v_cvt_pk_bf16_f32 v149, v168, v169
	v_lshl_add_u64 v[168:169], v[158:159], 1, s[42:43]
	s_waitcnt lgkmcnt(0)
	s_mul_i32 s65, s64, 0
	s_add_u32 s100, s60, s65
	s_addc_u32 s101, s61, 0
	global_store_dwordx4 v177, v[196:199], s[100:101]
	ds_write_b128 v175, v[146:149]
	ds_read_b128 v[200:203], v176
	v_add_u32_e32 v158, s12, v158
	s_nop 0
	v_fmamk_f32 v146, v167, 0x3a800000, v213
	v_rsq_f32_e32 v160, v146
	s_nop 0
	v_mul_f32_e32 v162, 0xbfb8aa3b, v160
	v_pk_fma_f32 v[168:169], v[94:95], v[162:163], v[156:157] op_sel_hi:[1,0,1]
	v_pk_fma_f32 v[170:171], v[96:97], v[162:163], v[154:155] op_sel_hi:[1,0,1]
	v_exp_f32_e32 v168, v168
	v_exp_f32_e32 v169, v169
	v_exp_f32_e32 v170, v170
	v_exp_f32_e32 v171, v171
	v_pk_fma_f32 v[146:147], v[94:95], v[160:161], v[138:139] op_sel_hi:[1,0,1]
	v_pk_add_f32 v[168:169], v[168:169], 1.0 op_sel_hi:[1,0]
	v_pk_fma_f32 v[148:149], v[90:91], v[160:161], v[142:143] op_sel_hi:[1,0,1]
	v_rcp_f32_e32 v168, v168
	v_rcp_f32_e32 v169, v169
	v_pk_add_f32 v[170:171], v[170:171], 1.0 op_sel_hi:[1,0]
	v_pk_mul_f32 v[146:147], v[146:147], v[148:149]
	v_rcp_f32_e32 v170, v170
	v_rcp_f32_e32 v171, v171
	v_pk_mul_f32 v[146:147], v[146:147], v[168:169]
	v_pk_fma_f32 v[148:149], v[96:97], v[160:161], v[140:141] op_sel_hi:[1,0,1]
	v_pk_fma_f32 v[168:169], v[92:93], v[160:161], v[144:145] op_sel_hi:[1,0,1]
	v_pk_fma_f32 v[172:173], v[88:89], v[162:163], v[150:151] op_sel_hi:[1,0,1]
	v_pk_mul_f32 v[148:149], v[148:149], v[168:169]
	v_exp_f32_e32 v172, v172
	v_pk_mul_f32 v[148:149], v[148:149], v[170:171]
	v_pk_fma_f32 v[170:171], v[86:87], v[162:163], v[152:153] op_sel_hi:[1,0,1]
	v_exp_f32_e32 v173, v173
	v_exp_f32_e32 v170, v170
	v_exp_f32_e32 v171, v171
	v_cvt_pk_bf16_f32 v146, v146, v147
	v_pk_add_f32 v[172:173], v[172:173], 1.0 op_sel_hi:[1,0]
	v_cvt_pk_bf16_f32 v147, v148, v149
	v_pk_add_f32 v[170:171], v[170:171], 1.0 op_sel_hi:[1,0]
	v_pk_fma_f32 v[148:149], v[86:87], v[160:161], v[130:131] op_sel_hi:[1,0,1]
	v_rcp_f32_e32 v170, v170
	v_rcp_f32_e32 v171, v171
	v_pk_fma_f32 v[168:169], v[82:83], v[160:161], v[134:135] op_sel_hi:[1,0,1]
	v_rcp_f32_e32 v172, v172
	v_rcp_f32_e32 v173, v173
	v_pk_mul_f32 v[148:149], v[148:149], v[168:169]
	v_pk_fma_f32 v[168:169], v[88:89], v[160:161], v[132:133] op_sel_hi:[1,0,1]
	v_pk_mul_f32 v[148:149], v[148:149], v[170:171]
	v_pk_fma_f32 v[170:171], v[84:85], v[160:161], v[136:137] op_sel_hi:[1,0,1]
	v_cvt_pk_bf16_f32 v148, v148, v149
	s_nop 0
	v_pk_mul_f32 v[168:169], v[168:169], v[170:171]
	s_nop 0
	v_pk_mul_f32 v[168:169], v[168:169], v[172:173]
	s_nop 0
	v_cvt_pk_bf16_f32 v149, v168, v169
	v_lshl_add_u64 v[168:169], v[158:159], 1, s[42:43]
	s_waitcnt lgkmcnt(0)
	s_mul_i32 s65, s64, 1
	s_add_u32 s100, s60, s65
	s_addc_u32 s101, s61, 0
	global_store_dwordx4 v177, v[200:203], s[100:101]
	ds_write_b128 v175, v[146:149]
	ds_read_b128 v[196:199], v176
	v_add_u32_e32 v158, s12, v158
	s_nop 0
	v_fmamk_f32 v146, v166, 0x3a800000, v213
	v_rsq_f32_e32 v160, v146
	s_nop 0
	v_mul_f32_e32 v162, 0xbfb8aa3b, v160
	v_pk_fma_f32 v[166:167], v[78:79], v[162:163], v[156:157] op_sel_hi:[1,0,1]
	v_pk_fma_f32 v[168:169], v[80:81], v[162:163], v[154:155] op_sel_hi:[1,0,1]
	v_exp_f32_e32 v166, v166
	v_exp_f32_e32 v167, v167
	v_exp_f32_e32 v168, v168
	v_exp_f32_e32 v169, v169
	v_pk_fma_f32 v[146:147], v[78:79], v[160:161], v[138:139] op_sel_hi:[1,0,1]
	v_pk_add_f32 v[166:167], v[166:167], 1.0 op_sel_hi:[1,0]
	v_pk_fma_f32 v[148:149], v[74:75], v[160:161], v[142:143] op_sel_hi:[1,0,1]
	v_rcp_f32_e32 v166, v166
	v_rcp_f32_e32 v167, v167
	v_pk_add_f32 v[168:169], v[168:169], 1.0 op_sel_hi:[1,0]
	v_pk_mul_f32 v[146:147], v[146:147], v[148:149]
	v_rcp_f32_e32 v168, v168
	v_rcp_f32_e32 v169, v169
	v_pk_mul_f32 v[146:147], v[146:147], v[166:167]
	v_pk_fma_f32 v[148:149], v[80:81], v[160:161], v[140:141] op_sel_hi:[1,0,1]
	v_pk_fma_f32 v[166:167], v[76:77], v[160:161], v[144:145] op_sel_hi:[1,0,1]
	v_pk_fma_f32 v[170:171], v[72:73], v[162:163], v[150:151] op_sel_hi:[1,0,1]
	v_pk_mul_f32 v[148:149], v[148:149], v[166:167]
	v_exp_f32_e32 v170, v170
	v_pk_mul_f32 v[148:149], v[148:149], v[168:169]
	v_pk_fma_f32 v[168:169], v[70:71], v[162:163], v[152:153] op_sel_hi:[1,0,1]
	v_exp_f32_e32 v171, v171
	v_exp_f32_e32 v168, v168
	v_exp_f32_e32 v169, v169
	v_cvt_pk_bf16_f32 v146, v146, v147
	v_pk_add_f32 v[170:171], v[170:171], 1.0 op_sel_hi:[1,0]
	v_cvt_pk_bf16_f32 v147, v148, v149
	v_pk_add_f32 v[168:169], v[168:169], 1.0 op_sel_hi:[1,0]
	v_pk_fma_f32 v[148:149], v[70:71], v[160:161], v[130:131] op_sel_hi:[1,0,1]
	v_rcp_f32_e32 v168, v168
	v_rcp_f32_e32 v169, v169
	v_pk_fma_f32 v[166:167], v[66:67], v[160:161], v[134:135] op_sel_hi:[1,0,1]
	v_rcp_f32_e32 v170, v170
	v_rcp_f32_e32 v171, v171
	v_pk_mul_f32 v[148:149], v[148:149], v[166:167]
	v_pk_fma_f32 v[166:167], v[72:73], v[160:161], v[132:133] op_sel_hi:[1,0,1]
	v_pk_mul_f32 v[148:149], v[148:149], v[168:169]
	v_pk_fma_f32 v[168:169], v[68:69], v[160:161], v[136:137] op_sel_hi:[1,0,1]
	v_cvt_pk_bf16_f32 v148, v148, v149
	s_nop 0
	v_pk_mul_f32 v[166:167], v[166:167], v[168:169]
	s_nop 0
	v_pk_mul_f32 v[166:167], v[166:167], v[170:171]
	s_nop 0
	v_cvt_pk_bf16_f32 v149, v166, v167
	v_lshl_add_u64 v[166:167], v[158:159], 1, s[42:43]
	s_waitcnt lgkmcnt(0)
; __device__ __forceinline__ unsigned cvt_pk_bf16(float lo, float hi) { unsigned r; asm volatile("v_cvt_pk_bf16_f32 %0, %1, %2" : "=v"(r) : "v"(lo), "v"(hi)); return r; }
;     __device__ __forceinline__ void operator()(const f32x4 (&acc)[2][2][4][2], const Unit& u, int wr, int wc, int fr, int fq) const {
;     ...
;             for (int m = 0; m < 4; ++m) {
;                 const int row = row0 + ai * HALF + m * 16;
;                 const float rs = __builtin_amdgcn_rsqf(sq[ai][m] * (1.0f / 1024.0f) + RMS_EPS_F), rz = rs * NL2E;
;                 unsigned w[4];
; #pragma unroll
;                 for (int p = 0; p < 4; ++p) {
;                     const f32x4 a0 = acc[ai][0][m][p >> 1], a1 = acc[ai][1][m][p >> 1];
;                     const f32x2 c0 = (p & 1) ? (f32x2){a0[2], a0[3]} : (f32x2){a0[0], a0[1]}, c1 = (p & 1) ? (f32x2){a1[2], a1[3]} : (f32x2){a1[0], a1[1]};
;                     const f32x2 v0 = c0 * rs + b0[p], v1 = c1 * rs + b1[p];
;                     const f32x2 t = (MODE == 0 ? c0 : c1) * rz + bz[p];
;                     f32x2 d; d.x = __builtin_amdgcn_exp2f(t.x); d.y = __builtin_amdgcn_exp2f(t.y); d = d + 1.0f;
;                     f32x2 r; r.x = __builtin_amdgcn_rcpf(d.x); r.y = __builtin_amdgcn_rcpf(d.y);
;                     const f32x2 o = (MODE == 0) ? (v0 * v1) * r : v0 * r;
;                     w[p] = cvt_pk_bf16(o.x, o.y);
;                 }
;                 u32x4 wv; wv.x = w[0]; wv.y = w[1]; wv.z = w[2]; wv.w = w[3];
;                 *(u32x4*)(O + ((unsigned)row * (unsigned)ldc + (unsigned)ocol)) = wv;
	s_mul_i32 s65, s64, 2
	s_add_u32 s100, s60, s65
	s_addc_u32 s101, s61, 0
	global_store_dwordx4 v177, v[196:199], s[100:101]
	ds_write_b128 v175, v[146:149]
	ds_read_b128 v[200:203], v176
	v_add_u32_e32 v158, s17, v158
	s_nop 0
	v_fmamk_f32 v146, v165, 0x3a800000, v213
	v_rsq_f32_e32 v160, v146
	s_nop 0
	v_mul_f32_e32 v162, 0xbfb8aa3b, v160
	v_pk_fma_f32 v[166:167], v[62:63], v[162:163], v[156:157] op_sel_hi:[1,0,1]
	v_pk_fma_f32 v[168:169], v[64:65], v[162:163], v[154:155] op_sel_hi:[1,0,1]
	v_exp_f32_e32 v166, v166
	v_exp_f32_e32 v167, v167
	v_exp_f32_e32 v168, v168
	v_exp_f32_e32 v169, v169
	v_pk_fma_f32 v[146:147], v[62:63], v[160:161], v[138:139] op_sel_hi:[1,0,1]
	v_pk_add_f32 v[166:167], v[166:167], 1.0 op_sel_hi:[1,0]
	v_pk_fma_f32 v[148:149], v[58:59], v[160:161], v[142:143] op_sel_hi:[1,0,1]
	v_rcp_f32_e32 v166, v166
	v_rcp_f32_e32 v167, v167
	v_pk_add_f32 v[168:169], v[168:169], 1.0 op_sel_hi:[1,0]
	v_pk_mul_f32 v[146:147], v[146:147], v[148:149]
	v_rcp_f32_e32 v168, v168
	v_rcp_f32_e32 v169, v169
	v_pk_mul_f32 v[146:147], v[146:147], v[166:167]
	v_pk_fma_f32 v[148:149], v[64:65], v[160:161], v[140:141] op_sel_hi:[1,0,1]
	v_pk_fma_f32 v[166:167], v[60:61], v[160:161], v[144:145] op_sel_hi:[1,0,1]
	v_pk_fma_f32 v[170:171], v[56:57], v[162:163], v[150:151] op_sel_hi:[1,0,1]
	v_pk_mul_f32 v[148:149], v[148:149], v[166:167]
	v_exp_f32_e32 v170, v170
	v_pk_mul_f32 v[148:149], v[148:149], v[168:169]
	v_pk_fma_f32 v[168:169], v[54:55], v[162:163], v[152:153] op_sel_hi:[1,0,1]
	v_exp_f32_e32 v171, v171
	v_exp_f32_e32 v168, v168
	v_exp_f32_e32 v169, v169
	v_cvt_pk_bf16_f32 v146, v146, v147
	v_pk_add_f32 v[170:171], v[170:171], 1.0 op_sel_hi:[1,0]
	v_cvt_pk_bf16_f32 v147, v148, v149
	v_pk_add_f32 v[168:169], v[168:169], 1.0 op_sel_hi:[1,0]
	v_pk_fma_f32 v[148:149], v[54:55], v[160:161], v[130:131] op_sel_hi:[1,0,1]
	v_rcp_f32_e32 v168, v168
	v_rcp_f32_e32 v169, v169
	v_pk_fma_f32 v[166:167], v[50:51], v[160:161], v[134:135] op_sel_hi:[1,0,1]
	v_rcp_f32_e32 v170, v170
	v_rcp_f32_e32 v171, v171
	v_pk_mul_f32 v[148:149], v[148:149], v[166:167]
	v_pk_fma_f32 v[166:167], v[56:57], v[160:161], v[132:133] op_sel_hi:[1,0,1]
	v_pk_mul_f32 v[148:149], v[148:149], v[168:169]
	v_pk_fma_f32 v[168:169], v[52:53], v[160:161], v[136:137] op_sel_hi:[1,0,1]
	v_cvt_pk_bf16_f32 v148, v148, v149
	s_nop 0
	v_pk_mul_f32 v[166:167], v[166:167], v[168:169]
	s_nop 0
	v_pk_mul_f32 v[166:167], v[166:167], v[170:171]
	s_nop 0
	v_cvt_pk_bf16_f32 v149, v166, v167
	v_lshl_add_u64 v[166:167], v[158:159], 1, s[42:43]
	s_waitcnt lgkmcnt(0)
	s_mul_i32 s65, s64, 3
	s_add_u32 s100, s60, s65
	s_addc_u32 s101, s61, 0
	global_store_dwordx4 v177, v[200:203], s[100:101]
	ds_write_b128 v175, v[146:149]
	ds_read_b128 v[196:199], v176
	v_add_u32_e32 v158, s12, v158
	s_nop 0
	v_fmamk_f32 v146, v164, 0x3a800000, v213
	v_rsq_f32_e32 v160, v146
	s_nop 0
	v_mul_f32_e32 v162, 0xbfb8aa3b, v160
	v_pk_fma_f32 v[164:165], v[46:47], v[162:163], v[156:157] op_sel_hi:[1,0,1]
	v_pk_fma_f32 v[166:167], v[48:49], v[162:163], v[154:155] op_sel_hi:[1,0,1]
	v_exp_f32_e32 v164, v164
	v_exp_f32_e32 v165, v165
	v_exp_f32_e32 v166, v166
	v_exp_f32_e32 v167, v167
	v_pk_fma_f32 v[146:147], v[46:47], v[160:161], v[138:139] op_sel_hi:[1,0,1]
	v_pk_add_f32 v[164:165], v[164:165], 1.0 op_sel_hi:[1,0]
	v_pk_fma_f32 v[148:149], v[42:43], v[160:161], v[142:143] op_sel_hi:[1,0,1]
	v_rcp_f32_e32 v164, v164
	v_rcp_f32_e32 v165, v165
	v_pk_add_f32 v[166:167], v[166:167], 1.0 op_sel_hi:[1,0]
	v_pk_mul_f32 v[146:147], v[146:147], v[148:149]
	v_rcp_f32_e32 v166, v166
	v_rcp_f32_e32 v167, v167
	v_pk_mul_f32 v[146:147], v[146:147], v[164:165]
	v_pk_fma_f32 v[148:149], v[48:49], v[160:161], v[140:141] op_sel_hi:[1,0,1]
	v_pk_fma_f32 v[164:165], v[44:45], v[160:161], v[144:145] op_sel_hi:[1,0,1]
	v_pk_fma_f32 v[168:169], v[40:41], v[162:163], v[150:151] op_sel_hi:[1,0,1]
	v_pk_mul_f32 v[148:149], v[148:149], v[164:165]
	v_exp_f32_e32 v168, v168
	v_pk_mul_f32 v[148:149], v[148:149], v[166:167]
	v_pk_fma_f32 v[166:167], v[38:39], v[162:163], v[152:153] op_sel_hi:[1,0,1]
	v_exp_f32_e32 v169, v169
	v_exp_f32_e32 v166, v166
	v_exp_f32_e32 v167, v167
	v_cvt_pk_bf16_f32 v146, v146, v147
	v_pk_add_f32 v[168:169], v[168:169], 1.0 op_sel_hi:[1,0]
	v_cvt_pk_bf16_f32 v147, v148, v149
	v_pk_add_f32 v[166:167], v[166:167], 1.0 op_sel_hi:[1,0]
	v_pk_fma_f32 v[148:149], v[38:39], v[160:161], v[130:131] op_sel_hi:[1,0,1]
	v_rcp_f32_e32 v166, v166
	v_rcp_f32_e32 v167, v167
	v_pk_fma_f32 v[164:165], v[34:35], v[160:161], v[134:135] op_sel_hi:[1,0,1]
	v_rcp_f32_e32 v168, v168
	v_rcp_f32_e32 v169, v169
	v_pk_mul_f32 v[148:149], v[148:149], v[164:165]
	v_pk_fma_f32 v[164:165], v[40:41], v[160:161], v[132:133] op_sel_hi:[1,0,1]
	v_pk_mul_f32 v[148:149], v[148:149], v[166:167]
	v_pk_fma_f32 v[166:167], v[36:37], v[160:161], v[136:137] op_sel_hi:[1,0,1]
	v_cvt_pk_bf16_f32 v148, v148, v149
	s_nop 0
	v_pk_mul_f32 v[164:165], v[164:165], v[166:167]
	s_nop 0
	v_pk_mul_f32 v[164:165], v[164:165], v[168:169]
	s_nop 0
	v_cvt_pk_bf16_f32 v149, v164, v165
	v_lshl_add_u64 v[164:165], v[158:159], 1, s[42:43]
	s_waitcnt lgkmcnt(0)
; __device__ __forceinline__ unsigned cvt_pk_bf16(float lo, float hi) { unsigned r; asm volatile("v_cvt_pk_bf16_f32 %0, %1, %2" : "=v"(r) : "v"(lo), "v"(hi)); return r; }
;     __device__ __forceinline__ void operator()(const f32x4 (&acc)[2][2][4][2], const Unit& u, int wr, int wc, int fr, int fq) const {
;     ...
;             for (int m = 0; m < 4; ++m) {
;                 const int row = row0 + ai * HALF + m * 16;
;                 const float rs = __builtin_amdgcn_rsqf(sq[ai][m] * (1.0f / 1024.0f) + RMS_EPS_F), rz = rs * NL2E;
;                 unsigned w[4];
; #pragma unroll
;                 for (int p = 0; p < 4; ++p) {
;                     const f32x4 a0 = acc[ai][0][m][p >> 1], a1 = acc[ai][1][m][p >> 1];
;                     const f32x2 c0 = (p & 1) ? (f32x2){a0[2], a0[3]} : (f32x2){a0[0], a0[1]}, c1 = (p & 1) ? (f32x2){a1[2], a1[3]} : (f32x2){a1[0], a1[1]};
;                     const f32x2 v0 = c0 * rs + b0[p], v1 = c1 * rs + b1[p];
;                     const f32x2 t = (MODE == 0 ? c0 : c1) * rz + bz[p];
;                     f32x2 d; d.x = __builtin_amdgcn_exp2f(t.x); d.y = __builtin_amdgcn_exp2f(t.y); d = d + 1.0f;
;                     f32x2 r; r.x = __builtin_amdgcn_rcpf(d.x); r.y = __builtin_amdgcn_rcpf(d.y);
;                     const f32x2 o = (MODE == 0) ? (v0 * v1) * r : v0 * r;
;                     w[p] = cvt_pk_bf16(o.x, o.y);
;                 }
;                 u32x4 wv; wv.x = w[0]; wv.y = w[1]; wv.z = w[2]; wv.w = w[3];
;                 *(u32x4*)(O + ((unsigned)row * (unsigned)ldc + (unsigned)ocol)) = wv;
	s_mul_i32 s65, s64, 8
	s_add_u32 s100, s60, s65
	s_addc_u32 s101, s61, 0
	global_store_dwordx4 v177, v[196:199], s[100:101]
	ds_write_b128 v175, v[146:149]
	ds_read_b128 v[200:203], v176
	v_add_u32_e32 v158, s12, v158
	s_nop 0
	v_fmamk_f32 v146, v163, 0x3a800000, v213
	v_rsq_f32_e32 v160, v146
	s_nop 0
	v_mul_f32_e32 v162, 0xbfb8aa3b, v160
	v_pk_fma_f32 v[164:165], v[30:31], v[162:163], v[156:157] op_sel_hi:[1,0,1]
	v_pk_fma_f32 v[166:167], v[32:33], v[162:163], v[154:155] op_sel_hi:[1,0,1]
	v_exp_f32_e32 v164, v164
	v_exp_f32_e32 v165, v165
	v_exp_f32_e32 v166, v166
	v_exp_f32_e32 v167, v167
	v_pk_fma_f32 v[146:147], v[30:31], v[160:161], v[138:139] op_sel_hi:[1,0,1]
	v_pk_add_f32 v[164:165], v[164:165], 1.0 op_sel_hi:[1,0]
	v_pk_fma_f32 v[148:149], v[26:27], v[160:161], v[142:143] op_sel_hi:[1,0,1]
	v_rcp_f32_e32 v164, v164
	v_rcp_f32_e32 v165, v165
	v_pk_add_f32 v[166:167], v[166:167], 1.0 op_sel_hi:[1,0]
	v_pk_mul_f32 v[146:147], v[146:147], v[148:149]
	v_rcp_f32_e32 v166, v166
	v_rcp_f32_e32 v167, v167
	v_pk_mul_f32 v[146:147], v[146:147], v[164:165]
	v_pk_fma_f32 v[148:149], v[32:33], v[160:161], v[140:141] op_sel_hi:[1,0,1]
	v_pk_fma_f32 v[164:165], v[28:29], v[160:161], v[144:145] op_sel_hi:[1,0,1]
	v_cvt_pk_bf16_f32 v146, v146, v147
	s_nop 0
	v_pk_mul_f32 v[148:149], v[148:149], v[164:165]
	v_pk_fma_f32 v[164:165], v[18:19], v[160:161], v[134:135] op_sel_hi:[1,0,1]
	v_pk_mul_f32 v[148:149], v[148:149], v[166:167]
	v_pk_fma_f32 v[166:167], v[22:23], v[162:163], v[152:153] op_sel_hi:[1,0,1]
	v_pk_fma_f32 v[162:163], v[24:25], v[162:163], v[150:151] op_sel_hi:[1,0,1]
	v_exp_f32_e32 v166, v166
	v_exp_f32_e32 v167, v167
	v_exp_f32_e32 v162, v162
	v_exp_f32_e32 v163, v163
	v_cvt_pk_bf16_f32 v147, v148, v149
	v_pk_add_f32 v[166:167], v[166:167], 1.0 op_sel_hi:[1,0]
	v_pk_fma_f32 v[148:149], v[22:23], v[160:161], v[130:131] op_sel_hi:[1,0,1]
	v_rcp_f32_e32 v166, v166
	v_rcp_f32_e32 v167, v167
	v_pk_add_f32 v[162:163], v[162:163], 1.0 op_sel_hi:[1,0]
	v_pk_mul_f32 v[148:149], v[148:149], v[164:165]
	v_rcp_f32_e32 v162, v162
	v_rcp_f32_e32 v163, v163
	v_pk_mul_f32 v[148:149], v[148:149], v[166:167]
	v_pk_fma_f32 v[164:165], v[24:25], v[160:161], v[132:133] op_sel_hi:[1,0,1]
	v_pk_fma_f32 v[166:167], v[20:21], v[160:161], v[136:137] op_sel_hi:[1,0,1]
	v_cvt_pk_bf16_f32 v148, v148, v149
	s_nop 0
	v_pk_mul_f32 v[164:165], v[164:165], v[166:167]
	s_nop 0
	v_pk_mul_f32 v[162:163], v[164:165], v[162:163]
	s_nop 0
	v_cvt_pk_bf16_f32 v149, v162, v163
	v_lshl_add_u64 v[162:163], v[158:159], 1, s[42:43]
	s_waitcnt lgkmcnt(0)
	s_mul_i32 s65, s64, 9
	s_add_u32 s100, s60, s65
	s_addc_u32 s101, s61, 0
	global_store_dwordx4 v177, v[200:203], s[100:101]
	ds_write_b128 v175, v[146:149]
	ds_read_b128 v[196:199], v176
	s_nop 1
	v_fmamk_f32 v146, v161, 0x3a800000, v213
	v_rsq_f32_e32 v146, v146
	s_nop 0
	v_mul_f32_e32 v148, 0xbfb8aa3b, v146
	v_pk_fma_f32 v[138:139], v[14:15], v[146:147], v[138:139] op_sel_hi:[1,0,1]
	v_pk_fma_f32 v[142:143], v[10:11], v[146:147], v[142:143] op_sel_hi:[1,0,1]
	v_pk_fma_f32 v[156:157], v[14:15], v[148:149], v[156:157] op_sel_hi:[1,0,1]
	v_pk_mul_f32 v[138:139], v[138:139], v[142:143]
	v_pk_fma_f32 v[142:143], v[12:13], v[146:147], v[144:145] op_sel_hi:[1,0,1]
	v_pk_fma_f32 v[144:145], v[16:17], v[148:149], v[154:155] op_sel_hi:[1,0,1]
	v_exp_f32_e32 v156, v156
	v_exp_f32_e32 v157, v157
	v_exp_f32_e32 v144, v144
	v_exp_f32_e32 v145, v145
	v_pk_fma_f32 v[140:141], v[16:17], v[146:147], v[140:141] op_sel_hi:[1,0,1]
	v_pk_add_f32 v[156:157], v[156:157], 1.0 op_sel_hi:[1,0]
	v_pk_mul_f32 v[140:141], v[140:141], v[142:143]
	v_pk_add_f32 v[144:145], v[144:145], 1.0 op_sel_hi:[1,0]
	v_rcp_f32_e32 v156, v156
	v_rcp_f32_e32 v157, v157
	v_rcp_f32_e32 v144, v144
	v_rcp_f32_e32 v145, v145
	v_pk_fma_f32 v[130:131], v[6:7], v[146:147], v[130:131] op_sel_hi:[1,0,1]
	v_pk_mul_f32 v[138:139], v[138:139], v[156:157]
	v_pk_fma_f32 v[134:135], v[2:3], v[146:147], v[134:135] op_sel_hi:[1,0,1]
	v_pk_mul_f32 v[140:141], v[140:141], v[144:145]
	v_cvt_pk_bf16_f32 v138, v138, v139
	v_pk_mul_f32 v[130:131], v[130:131], v[134:135]
	v_cvt_pk_bf16_f32 v139, v140, v141
	v_pk_fma_f32 v[140:141], v[6:7], v[148:149], v[152:153] op_sel_hi:[1,0,1]
	v_pk_fma_f32 v[134:135], v[8:9], v[148:149], v[150:151] op_sel_hi:[1,0,1]
	v_exp_f32_e32 v140, v140
	v_exp_f32_e32 v141, v141
	v_exp_f32_e32 v134, v134
	v_exp_f32_e32 v135, v135
	v_pk_add_f32 v[140:141], v[140:141], 1.0 op_sel_hi:[1,0]
	s_nop 0
	v_rcp_f32_e32 v140, v140
	v_rcp_f32_e32 v141, v141
	v_pk_add_f32 v[134:135], v[134:135], 1.0 op_sel_hi:[1,0]
	v_pk_mul_f32 v[130:131], v[130:131], v[140:141]
	v_rcp_f32_e32 v134, v134
	v_rcp_f32_e32 v135, v135
	v_cvt_pk_bf16_f32 v140, v130, v131
	v_pk_fma_f32 v[130:131], v[8:9], v[146:147], v[132:133] op_sel_hi:[1,0,1]
	v_pk_fma_f32 v[132:133], v[4:5], v[146:147], v[136:137] op_sel_hi:[1,0,1]
	s_nop 0
	v_pk_mul_f32 v[130:131], v[130:131], v[132:133]
	s_nop 0
	v_pk_mul_f32 v[130:131], v[130:131], v[134:135]
	s_nop 0
	v_cvt_pk_bf16_f32 v141, v130, v131
	v_add_u32_e32 v130, s12, v158
	v_mov_b32_e32 v131, v0
	v_lshl_add_u64 v[130:131], v[130:131], 1, s[42:43]
	s_mov_b64 s[42:43], 0
	s_waitcnt lgkmcnt(0)
	s_mul_i32 s65, s64, 10
	s_add_u32 s100, s60, s65
	s_addc_u32 s101, s61, 0
	global_store_dwordx4 v177, v[196:199], s[100:101]
	ds_write_b128 v175, v[138:141]
	ds_read_b128 v[200:203], v176
	s_waitcnt lgkmcnt(0)
	s_mul_i32 s65, s64, 11
	s_add_u32 s100, s60, s65
	s_addc_u32 s101, s61, 0
	global_store_dwordx4 v177, v[200:203], s[100:101]
